# first grid barrier (after phase 0): cooperative-groups sync replaced by per-workgroup 64-bit flag slots (release fence, agent-scope flag store, 64 lanes poll all 256 slots, acquire); flags cleared at
# speedup vs baseline: 1.0132x; 1.0000x over previous
.LBB0_61:
	s_cbranch_execz .LBB0_73
	v_lshrrev_b32_e32 v1, 20, v0
	v_lshrrev_b32_e32 v2, 10, v0
	v_or_b32_e32 v1, v2, v1
	s_movk_i32 s0, 0x3ff
	v_and_or_b32 v1, v1, s0, v192
	v_cmp_eq_u32_e32 vcc, 0, v1
	s_barrier
	s_and_saveexec_b64 s[0:1], vcc
	s_cbranch_execz .LBB0_72
	buffer_wbl2 sc1
	s_waitcnt vmcnt(0)
	s_load_dwordx2 s[4:5], s[74:75], 0xb0
	s_lshl_b32 s3, s2, 3
	v_mov_b32_e32 v1, s3
	s_mov_b32 s6, 0x5a17c0de
	s_mov_b32 s7, 0xa5e83f21
	v_mov_b32_e32 v2, s6
	v_mov_b32_e32 v3, s7
	s_waitcnt lgkmcnt(0)
	s_add_u32 s4, s4, 0x1ee16000
	s_addc_u32 s5, s5, 0
	global_store_dwordx2 v1, v[2:3], s[4:5] sc1
	s_mov_b64 exec, -1
	v_mbcnt_lo_u32_b32 v1, -1, 0
	v_mbcnt_hi_u32_b32 v1, -1, v1
	v_lshlrev_b32_e32 v1, 3, v1
.Lgb0_poll:
	global_load_dwordx2 v[4:5], v1, s[4:5] sc1
	global_load_dwordx2 v[6:7], v1, s[4:5] offset:512 sc1
	global_load_dwordx2 v[8:9], v1, s[4:5] offset:1024 sc1
	global_load_dwordx2 v[10:11], v1, s[4:5] offset:1536 sc1
	s_waitcnt vmcnt(0)
	v_cmp_ne_u32_e32 vcc, s6, v4
	v_cmp_ne_u32_e64 s[8:9], s7, v5
	s_or_b64 s[10:11], vcc, s[8:9]
	v_cmp_ne_u32_e32 vcc, s6, v6
	v_cmp_ne_u32_e64 s[8:9], s7, v7
	s_or_b64 s[10:11], s[10:11], vcc
	s_or_b64 s[10:11], s[10:11], s[8:9]
	v_cmp_ne_u32_e32 vcc, s6, v8
	v_cmp_ne_u32_e64 s[8:9], s7, v9
	s_or_b64 s[10:11], s[10:11], vcc
	s_or_b64 s[10:11], s[10:11], s[8:9]
	v_cmp_ne_u32_e32 vcc, s6, v10
	v_cmp_ne_u32_e64 s[8:9], s7, v11
	s_or_b64 s[10:11], s[10:11], vcc
	s_or_b64 s[10:11], s[10:11], s[8:9]
	s_cmp_eq_u64 s[10:11], 0
	s_cbranch_scc1 .Lgb0_done
	s_sleep 1
	s_branch .Lgb0_poll
.Lgb0_done:
	buffer_inv sc1
	s_waitcnt vmcnt(0)
.LBB0_72:
	s_or_b64 exec, exec, s[0:1]
	s_barrier

.LBB0_800:
	v_readlane_b32 s4, v254, 30
	v_readlane_b32 s5, v254, 31
	v_readlane_b32 s3, v254, 0
	s_nop 7
	s_load_dwordx2 s[4:5], s[4:5], 0xb0
	s_lshl_b32 s3, s3, 3
	v_cmp_eq_u32_e32 vcc, 0, v192
	s_and_saveexec_b64 s[6:7], vcc
	s_cbranch_execz .Lgb0_exit
	v_mov_b32_e32 v2, s3
	v_mov_b32_e32 v4, 0
	v_mov_b32_e32 v5, 0
	s_waitcnt lgkmcnt(0)
	s_add_u32 s4, s4, 0x1ee16000
	s_addc_u32 s5, s5, 0
	global_store_dwordx2 v2, v[4:5], s[4:5] sc1
